# P5 epilogue: the final-gain vector loads issued during the last residual batch (were issued after the panel exchange and waited before the stores); on top of v83
# baseline (speedup 1.0000x reference)
;     __device__ __forceinline__ void operator()(f32x4 (&acc)[2][2][4][2], const Unit& u, int wr, int wc, int fr, int fq, LAS unsigned char* lds) const {
;     ...
;                 for (int m = 0; m < 4; ++m) { int rr_ = row0 + ai * HALF + m * 16; asm volatile("" : "+v"(rr_)); const float* xr = xp + (size_t)rr_ * DM + col0;
;                     float sq = 0.f;
; #pragma unroll
;                     for (int bj = 0; bj < 2; ++bj) { const f32x4 v0 = *(const f32x4*)(xr + bj * HALF) + gv[bj][0] * acc[ai][bj][m][0], v1 = *(const f32x4*)(xr + bj * HALF + 4) + gv[bj][1] * acc[ai][bj][m][1];
;                         acc[ai][bj][m][0] = v0; acc[ai][bj][m][1] = v1;
;                         sq += ((v0[0] * v0[0] + v0[1] * v0[1]) + (v0[2] * v0[2] + v0[3] * v0[3])) + ((v1[0] * v1[0] + v1[1] * v1[1]) + (v1[2] * v1[2] + v1[3] * v1[3])); }
;                     sq += __shfl_xor(sq, 16); sq += __shfl_xor(sq, 32);
;                     if (fq == 0) P[(ai * HALF + wr * 64 + m * 16 + fr) * 4 + wc] = sq; }
;     ...
;             f32x4 gf[2][2];
; #pragma unroll
;             for (int bj = 0; bj < 2; ++bj) { gf[bj][0] = *(const f32x4*)(gfin + col0 + bj * HALF); gf[bj][1] = *(const f32x4*)(gfin + col0 + bj * HALF + 4); }
.LBB0_1231:
	s_or_b64 exec, exec, s[4:5]
	global_load_dwordx4 v[218:221], v152, s[24:25]
	global_load_dwordx4 v[222:225], v152, s[24:25] offset:16
	global_load_dwordx4 v[226:229], v152, s[24:25] offset:512
	global_load_dwordx4 v[230:233], v152, s[24:25] offset:528
	v_add_u32_e32 v174, 0xb0, v158
	v_mov_b32_e32 v186, v174
	s_nop 0
	v_ashrrev_i32_e32 v187, 31, v186
	v_lshlrev_b64 v[186:187], 12, v[186:187]
	v_lshl_add_u64 v[186:187], s[36:37], 0, v[186:187]
	v_lshl_add_u64 v[198:199], v[186:187], 0, v[152:153]
	s_nop 0
	s_waitcnt vmcnt(3)
	v_pk_fma_f32 v[134:135], v[14:15], v[134:135], v[236:237]
	v_pk_fma_f32 v[132:133], v[12:13], v[132:133], v[234:235]
	s_waitcnt vmcnt(2)
	v_pk_fma_f32 v[130:131], v[10:11], v[130:131], v[240:241]
	v_pk_fma_f32 v[128:129], v[8:9], v[128:129], v[238:239]
	s_waitcnt vmcnt(1)
	v_pk_fma_f32 v[126:127], v[6:7], v[126:127], v[244:245]
	v_pk_fma_f32 v[124:125], v[4:5], v[124:125], v[242:243]
	s_waitcnt vmcnt(0)
	v_pk_fma_f32 v[118:119], v[2:3], v[118:119], v[248:249]
	v_pk_fma_f32 v[116:117], v[0:1], v[116:117], v[246:247]
	v_mul_f32_e32 v0, v133, v133
	v_mul_f32_e32 v1, v135, v135
	v_mul_f32_e32 v2, v129, v129
	v_mul_f32_e32 v3, v131, v131
	v_mul_f32_e32 v4, v125, v125
	v_mul_f32_e32 v5, v127, v127
	v_mul_f32_e32 v6, v117, v117
	v_mul_f32_e32 v7, v119, v119
	v_fmac_f32_e32 v0, v132, v132
	v_fmac_f32_e32 v1, v134, v134
	v_fmac_f32_e32 v2, v128, v128
	v_fmac_f32_e32 v3, v130, v130
	v_fmac_f32_e32 v4, v124, v124
	v_fmac_f32_e32 v5, v126, v126
	v_fmac_f32_e32 v6, v116, v116
	v_fmac_f32_e32 v7, v118, v118
	v_add_f32_e32 v0, v0, v1
	v_add_f32_e32 v1, v2, v3
	v_add_f32_e32 v2, v4, v5
	v_add_f32_e32 v3, v6, v7
	v_add_f32_e32 v0, v0, v1
	v_add_f32_e32 v1, v2, v3
	v_add_f32_e32 v0, v0, v1
	ds_bpermute_b32 v1, v177, v0
	s_waitcnt lgkmcnt(0)
	v_add_f32_e32 v0, v0, v1
	ds_bpermute_b32 v1, v178, v0
	s_and_saveexec_b64 s[4:5], vcc
	s_cbranch_execz .LBB0_1233
	s_waitcnt lgkmcnt(0)
	v_add_f32_e32 v0, v0, v1
	ds_write_b32 v113, v0 offset:2816

;     __device__ __forceinline__ void operator()(f32x4 (&acc)[2][2][4][2], const Unit& u, int wr, int wc, int fr, int fq, LAS unsigned char* lds) const {
;     ...
;         {
;             f32x4 gf[2][2];
; #pragma unroll
;             for (int bj = 0; bj < 2; ++bj) { gf[bj][0] = *(const f32x4*)(gfin + col0 + bj * HALF); gf[bj][1] = *(const f32x4*)(gfin + col0 + bj * HALF + 4); }
; #pragma unroll
;             for (int ai = 0; ai < 2; ++ai)
; #pragma unroll
;                 for (int m = 0; m < 4; ++m) { const float rs = S[ai * HALF + wr * 64 + m * 16 + fr]; int rr_ = row0 + ai * HALF + m * 16; asm volatile("" : "+v"(rr_)); float* orow = out + (size_t)rr_ * DM + col0;
; #pragma unroll
;                     for (int bj = 0; bj < 2; ++bj) { *(f32x4*)(orow + bj * HALF) = acc[ai][bj][m][0] * rs * gf[bj][0]; *(f32x4*)(orow + bj * HALF + 4) = acc[ai][bj][m][1] * rs * gf[bj][1]; } }
.LBB0_1249:
	s_or_b64 exec, exec, s[42:43]
	s_waitcnt lgkmcnt(0)
	s_barrier
	v_mov_b64_e32 v[12:13], v[218:219]
	v_mov_b64_e32 v[14:15], v[220:221]
	v_mov_b64_e32 v[8:9], v[222:223]
	v_mov_b64_e32 v[10:11], v[224:225]
	v_mov_b64_e32 v[4:5], v[226:227]
	v_mov_b64_e32 v[6:7], v[228:229]
	v_mov_b64_e32 v[0:1], v[230:231]
	v_mov_b64_e32 v[2:3], v[232:233]
	v_lshl_add_u32 v175, v159, 2, s67
	ds_read_b32 v160, v175
	ds_read_b32 v186, v175 offset:64
	v_ashrrev_i32_e32 v159, 31, v158
	v_lshlrev_b64 v[158:159], 12, v[158:159]
	v_lshl_add_u64 v[158:159], s[26:27], 0, v[158:159]
	v_lshl_add_u64 v[188:189], v[158:159], 0, v[152:153]
	s_waitcnt lgkmcnt(1)
	v_pk_mul_f32 v[158:159], v[162:163], v[160:161] op_sel_hi:[1,0]
	v_pk_mul_f32 v[142:143], v[142:143], v[160:161] op_sel_hi:[1,0]
	v_pk_mul_f32 v[140:141], v[140:141], v[160:161] op_sel_hi:[1,0]
	v_pk_mul_f32 v[138:139], v[138:139], v[160:161] op_sel_hi:[1,0]
	v_pk_mul_f32 v[136:137], v[136:137], v[160:161] op_sel_hi:[1,0]
	v_pk_mul_f32 v[122:123], v[122:123], v[160:161] op_sel_hi:[1,0]
	v_pk_mul_f32 v[120:121], v[120:121], v[160:161] op_sel_hi:[1,0]
	v_pk_mul_f32 v[114:115], v[114:115], v[160:161] op_sel_hi:[1,0]
	s_waitcnt lgkmcnt(0)
	v_pk_mul_f32 v[160:161], v[164:165], v[186:187] op_sel_hi:[1,0]
	v_pk_mul_f32 v[110:111], v[110:111], v[186:187] op_sel_hi:[1,0]
	v_pk_mul_f32 v[162:163], v[108:109], v[186:187] op_sel_hi:[1,0]
	v_pk_mul_f32 v[164:165], v[106:107], v[186:187] op_sel_hi:[1,0]
	v_pk_mul_f32 v[190:191], v[104:105], v[186:187] op_sel_hi:[1,0]
	v_pk_mul_f32 v[192:193], v[102:103], v[186:187] op_sel_hi:[1,0]
	v_pk_mul_f32 v[194:195], v[100:101], v[186:187] op_sel_hi:[1,0]
	v_pk_mul_f32 v[186:187], v[98:99], v[186:187] op_sel_hi:[1,0]
	s_and_b64 vcc, exec, s[0:1]
	s_mov_b64 s[0:1], -1
	s_waitcnt vmcnt(3)
	v_pk_mul_f32 v[100:101], v[14:15], v[142:143]
	v_pk_mul_f32 v[98:99], v[12:13], v[158:159]
	s_waitcnt vmcnt(2)
	v_pk_mul_f32 v[104:105], v[10:11], v[138:139]
	v_pk_mul_f32 v[102:103], v[8:9], v[140:141]
	s_waitcnt vmcnt(1)
	v_pk_mul_f32 v[108:109], v[6:7], v[122:123]
	v_pk_mul_f32 v[106:107], v[4:5], v[136:137]
	s_waitcnt vmcnt(0)
	v_pk_mul_f32 v[122:123], v[2:3], v[114:115]
	v_pk_mul_f32 v[120:121], v[0:1], v[120:121]
	global_store_dwordx4 v[188:189], v[98:101], off
	global_store_dwordx4 v[188:189], v[102:105], off offset:16
	global_store_dwordx4 v[188:189], v[106:109], off offset:512
	global_store_dwordx4 v[188:189], v[120:123], off offset:528
	ds_read_b32 v98, v175 offset:128
	v_ashrrev_i32_e32 v113, 31, v112
	v_lshlrev_b64 v[100:101], 12, v[112:113]
	v_lshl_add_u64 v[100:101], s[26:27], 0, v[100:101]
	v_pk_mul_f32 v[138:139], v[14:15], v[110:111]
	v_pk_mul_f32 v[136:137], v[12:13], v[160:161]
	v_lshl_add_u64 v[100:101], v[100:101], 0, v[152:153]
	v_pk_mul_f32 v[142:143], v[10:11], v[164:165]
	v_pk_mul_f32 v[140:141], v[8:9], v[162:163]
	v_pk_mul_f32 v[160:161], v[6:7], v[192:193]
	v_pk_mul_f32 v[158:159], v[4:5], v[190:191]
	v_pk_mul_f32 v[164:165], v[2:3], v[186:187]
	v_pk_mul_f32 v[162:163], v[0:1], v[194:195]
	global_store_dwordx4 v[100:101], v[136:139], off
	global_store_dwordx4 v[100:101], v[140:143], off offset:16
	global_store_dwordx4 v[100:101], v[158:161], off offset:512
	global_store_dwordx4 v[100:101], v[162:165], off offset:528
	s_waitcnt lgkmcnt(0)
	v_pk_mul_f32 v[94:95], v[94:95], v[98:99] op_sel_hi:[1,0]
	v_ashrrev_i32_e32 v97, 31, v96
	v_pk_mul_f32 v[106:107], v[84:85], v[98:99] op_sel_hi:[1,0]
	ds_read_b32 v108, v175 offset:192
	v_pk_mul_f32 v[84:85], v[14:15], v[94:95]
	v_lshlrev_b64 v[94:95], 12, v[96:97]
	v_pk_mul_f32 v[100:101], v[166:167], v[98:99] op_sel_hi:[1,0]
	v_lshl_add_u64 v[94:95], s[26:27], 0, v[94:95]
	v_pk_mul_f32 v[92:93], v[92:93], v[98:99] op_sel_hi:[1,0]
	v_pk_mul_f32 v[90:91], v[90:91], v[98:99] op_sel_hi:[1,0]
	v_pk_mul_f32 v[102:103], v[88:89], v[98:99] op_sel_hi:[1,0]
	v_pk_mul_f32 v[104:105], v[86:87], v[98:99] op_sel_hi:[1,0]
	v_pk_mul_f32 v[98:99], v[82:83], v[98:99] op_sel_hi:[1,0]
	v_pk_mul_f32 v[82:83], v[12:13], v[100:101]
	v_lshl_add_u64 v[94:95], v[94:95], 0, v[152:153]
	v_pk_mul_f32 v[88:89], v[10:11], v[90:91]
	v_pk_mul_f32 v[86:87], v[8:9], v[92:93]
	v_pk_mul_f32 v[92:93], v[6:7], v[104:105]
	v_pk_mul_f32 v[90:91], v[4:5], v[102:103]
	v_pk_mul_f32 v[100:101], v[2:3], v[98:99]
	v_pk_mul_f32 v[98:99], v[0:1], v[106:107]
	global_store_dwordx4 v[94:95], v[82:85], off
	global_store_dwordx4 v[94:95], v[86:89], off offset:16
	global_store_dwordx4 v[94:95], v[90:93], off offset:512
	global_store_dwordx4 v[94:95], v[98:101], off offset:528
	s_waitcnt lgkmcnt(0)
	v_pk_mul_f32 v[64:65], v[64:65], v[108:109] op_sel_hi:[1,0]
	v_ashrrev_i32_e32 v81, 31, v80
	v_lshlrev_b64 v[80:81], 12, v[80:81]
	v_lshl_add_u64 v[80:81], s[26:27], 0, v[80:81]
	v_pk_mul_f32 v[66:67], v[66:67], v[108:109] op_sel_hi:[1,0]
	v_lshl_add_u64 v[80:81], v[80:81], 0, v[152:153]
	v_pk_mul_f32 v[66:67], v[2:3], v[66:67]
	v_pk_mul_f32 v[64:65], v[0:1], v[64:65]
	global_store_dwordx4 v[80:81], v[64:67], off offset:528
	ds_read_b32 v64, v175 offset:512
	v_pk_mul_f32 v[76:77], v[76:77], v[108:109] op_sel_hi:[1,0]
	v_pk_mul_f32 v[78:79], v[78:79], v[108:109] op_sel_hi:[1,0]
	v_pk_mul_f32 v[72:73], v[72:73], v[108:109] op_sel_hi:[1,0]
	v_pk_mul_f32 v[74:75], v[74:75], v[108:109] op_sel_hi:[1,0]
	v_pk_mul_f32 v[68:69], v[68:69], v[108:109] op_sel_hi:[1,0]
	v_pk_mul_f32 v[70:71], v[70:71], v[108:109] op_sel_hi:[1,0]
	v_pk_mul_f32 v[78:79], v[14:15], v[78:79]
	v_pk_mul_f32 v[76:77], v[12:13], v[76:77]
	v_pk_mul_f32 v[74:75], v[10:11], v[74:75]
	v_pk_mul_f32 v[72:73], v[8:9], v[72:73]
	v_pk_mul_f32 v[70:71], v[6:7], v[70:71]
	v_pk_mul_f32 v[68:69], v[4:5], v[68:69]
	global_store_dwordx4 v[80:81], v[76:79], off
	global_store_dwordx4 v[80:81], v[72:75], off offset:16
	global_store_dwordx4 v[80:81], v[68:71], off offset:512
	s_waitcnt lgkmcnt(0)
;     __device__ __forceinline__ void operator()(f32x4 (&acc)[2][2][4][2], const Unit& u, int wr, int wc, int fr, int fq, LAS unsigned char* lds) const {
;     ...
;             for (int ai = 0; ai < 2; ++ai)
; #pragma unroll
;                 for (int m = 0; m < 4; ++m) { const float rs = S[ai * HALF + wr * 64 + m * 16 + fr]; int rr_ = row0 + ai * HALF + m * 16; asm volatile("" : "+v"(rr_)); float* orow = out + (size_t)rr_ * DM + col0;
; #pragma unroll
;                     for (int bj = 0; bj < 2; ++bj) { *(f32x4*)(orow + bj * HALF) = acc[ai][bj][m][0] * rs * gf[bj][0]; *(f32x4*)(orow + bj * HALF + 4) = acc[ai][bj][m][1] * rs * gf[bj][1]; } }
	v_pk_mul_f32 v[48:49], v[48:49], v[64:65] op_sel_hi:[1,0]
	v_ashrrev_i32_e32 v169, 31, v168
	v_lshlrev_b64 v[66:67], 12, v[168:169]
	v_lshl_add_u64 v[66:67], s[26:27], 0, v[66:67]
	v_pk_mul_f32 v[50:51], v[50:51], v[64:65] op_sel_hi:[1,0]
	v_lshl_add_u64 v[66:67], v[66:67], 0, v[152:153]
	v_pk_mul_f32 v[50:51], v[2:3], v[50:51]
	v_pk_mul_f32 v[48:49], v[0:1], v[48:49]
	global_store_dwordx4 v[66:67], v[48:51], off offset:528
	ds_read_b32 v48, v175 offset:576
	v_pk_mul_f32 v[60:61], v[60:61], v[64:65] op_sel_hi:[1,0]
	v_pk_mul_f32 v[62:63], v[62:63], v[64:65] op_sel_hi:[1,0]
	v_pk_mul_f32 v[56:57], v[56:57], v[64:65] op_sel_hi:[1,0]
	v_pk_mul_f32 v[58:59], v[58:59], v[64:65] op_sel_hi:[1,0]
	v_pk_mul_f32 v[52:53], v[52:53], v[64:65] op_sel_hi:[1,0]
	v_pk_mul_f32 v[54:55], v[54:55], v[64:65] op_sel_hi:[1,0]
	v_pk_mul_f32 v[62:63], v[14:15], v[62:63]
	v_pk_mul_f32 v[60:61], v[12:13], v[60:61]
	v_pk_mul_f32 v[58:59], v[10:11], v[58:59]
	v_pk_mul_f32 v[56:57], v[8:9], v[56:57]
	v_pk_mul_f32 v[54:55], v[6:7], v[54:55]
	v_pk_mul_f32 v[52:53], v[4:5], v[52:53]
	global_store_dwordx4 v[66:67], v[60:63], off
	global_store_dwordx4 v[66:67], v[56:59], off offset:16
	global_store_dwordx4 v[66:67], v[52:55], off offset:512
	s_waitcnt lgkmcnt(0)
	v_pk_mul_f32 v[32:33], v[32:33], v[48:49] op_sel_hi:[1,0]
	v_ashrrev_i32_e32 v171, 31, v170
	v_lshlrev_b64 v[50:51], 12, v[170:171]
	v_lshl_add_u64 v[50:51], s[26:27], 0, v[50:51]
	v_pk_mul_f32 v[34:35], v[34:35], v[48:49] op_sel_hi:[1,0]
	v_lshl_add_u64 v[50:51], v[50:51], 0, v[152:153]
	v_pk_mul_f32 v[34:35], v[2:3], v[34:35]
	v_pk_mul_f32 v[32:33], v[0:1], v[32:33]
	global_store_dwordx4 v[50:51], v[32:35], off offset:528
	ds_read_b32 v32, v175 offset:640
	v_pk_mul_f32 v[44:45], v[44:45], v[48:49] op_sel_hi:[1,0]
	v_pk_mul_f32 v[46:47], v[46:47], v[48:49] op_sel_hi:[1,0]
	v_pk_mul_f32 v[40:41], v[40:41], v[48:49] op_sel_hi:[1,0]
	v_pk_mul_f32 v[42:43], v[42:43], v[48:49] op_sel_hi:[1,0]
	v_pk_mul_f32 v[36:37], v[36:37], v[48:49] op_sel_hi:[1,0]
	v_pk_mul_f32 v[38:39], v[38:39], v[48:49] op_sel_hi:[1,0]
	v_pk_mul_f32 v[46:47], v[14:15], v[46:47]
	v_pk_mul_f32 v[44:45], v[12:13], v[44:45]
	v_pk_mul_f32 v[42:43], v[10:11], v[42:43]
	v_pk_mul_f32 v[40:41], v[8:9], v[40:41]
	v_pk_mul_f32 v[38:39], v[6:7], v[38:39]
	v_pk_mul_f32 v[36:37], v[4:5], v[36:37]
	global_store_dwordx4 v[50:51], v[44:47], off
	global_store_dwordx4 v[50:51], v[40:43], off offset:16
	global_store_dwordx4 v[50:51], v[36:39], off offset:512
	s_waitcnt lgkmcnt(0)
	v_pk_mul_f32 v[16:17], v[16:17], v[32:33] op_sel_hi:[1,0]
	v_ashrrev_i32_e32 v173, 31, v172
	v_lshlrev_b64 v[34:35], 12, v[172:173]
	v_lshl_add_u64 v[34:35], s[26:27], 0, v[34:35]
	v_pk_mul_f32 v[18:19], v[18:19], v[32:33] op_sel_hi:[1,0]
	v_lshl_add_u64 v[34:35], v[34:35], 0, v[152:153]
	v_pk_mul_f32 v[18:19], v[2:3], v[18:19]
	v_pk_mul_f32 v[16:17], v[0:1], v[16:17]
	global_store_dwordx4 v[34:35], v[16:19], off offset:528
	ds_read_b32 v16, v175 offset:704
	v_pk_mul_f32 v[28:29], v[28:29], v[32:33] op_sel_hi:[1,0]
	v_pk_mul_f32 v[30:31], v[30:31], v[32:33] op_sel_hi:[1,0]
	v_pk_mul_f32 v[24:25], v[24:25], v[32:33] op_sel_hi:[1,0]
	v_pk_mul_f32 v[26:27], v[26:27], v[32:33] op_sel_hi:[1,0]
	v_pk_mul_f32 v[20:21], v[20:21], v[32:33] op_sel_hi:[1,0]
	v_pk_mul_f32 v[22:23], v[22:23], v[32:33] op_sel_hi:[1,0]
	v_pk_mul_f32 v[30:31], v[14:15], v[30:31]
	v_pk_mul_f32 v[28:29], v[12:13], v[28:29]
	v_pk_mul_f32 v[26:27], v[10:11], v[26:27]
	v_pk_mul_f32 v[24:25], v[8:9], v[24:25]
	v_pk_mul_f32 v[22:23], v[6:7], v[22:23]
	v_pk_mul_f32 v[20:21], v[4:5], v[20:21]
	global_store_dwordx4 v[34:35], v[28:31], off
	global_store_dwordx4 v[34:35], v[24:27], off offset:16
	global_store_dwordx4 v[34:35], v[20:23], off offset:512
	s_nop 0
	v_ashrrev_i32_e32 v175, 31, v174
	v_lshlrev_b64 v[18:19], 12, v[174:175]
	v_lshl_add_u64 v[18:19], s[26:27], 0, v[18:19]
	s_waitcnt lgkmcnt(0)
	v_pk_mul_f32 v[20:21], v[132:133], v[16:17] op_sel_hi:[1,0]
	v_pk_mul_f32 v[22:23], v[134:135], v[16:17] op_sel_hi:[1,0]
	v_lshl_add_u64 v[18:19], v[18:19], 0, v[152:153]
	v_pk_mul_f32 v[14:15], v[14:15], v[22:23]
	v_pk_mul_f32 v[12:13], v[12:13], v[20:21]
	global_store_dwordx4 v[18:19], v[12:15], off
	s_nop 1
	v_pk_mul_f32 v[12:13], v[128:129], v[16:17] op_sel_hi:[1,0]
	v_pk_mul_f32 v[14:15], v[130:131], v[16:17] op_sel_hi:[1,0]
	v_pk_mul_f32 v[8:9], v[8:9], v[12:13]
	v_pk_mul_f32 v[10:11], v[10:11], v[14:15]
	global_store_dwordx4 v[18:19], v[8:11], off offset:16
	s_nop 1
	v_pk_mul_f32 v[8:9], v[124:125], v[16:17] op_sel_hi:[1,0]
	v_pk_mul_f32 v[10:11], v[126:127], v[16:17] op_sel_hi:[1,0]
	v_pk_mul_f32 v[4:5], v[4:5], v[8:9]
	v_pk_mul_f32 v[6:7], v[6:7], v[10:11]
	global_store_dwordx4 v[18:19], v[4:7], off offset:512
	s_nop 1
	v_pk_mul_f32 v[4:5], v[116:117], v[16:17] op_sel_hi:[1,0]
	v_pk_mul_f32 v[6:7], v[118:119], v[16:17] op_sel_hi:[1,0]
	v_pk_mul_f32 v[0:1], v[0:1], v[4:5]
	v_pk_mul_f32 v[2:3], v[2:3], v[6:7]
	global_store_dwordx4 v[18:19], v[0:3], off offset:528
	s_cbranch_vccnz .LBB0_1210
	s_andn2_b64 vcc, exec, s[8:9]
	s_cbranch_vccnz .LBB0_1209
	s_barrier
	s_branch .LBB0_1209
